# baseline (speedup 1.0000x reference)
; __device__ __forceinline__ unsigned cvt_pk(float lo, float hi) { unsigned r; asm("v_cvt_pk_bf16_f32 %0, %1, %2" : "=v"(r) : "v"(lo), "v"(hi)); return r; }
; __device__ __forceinline__ void attn_store(bf16_t* dst, const f32x4 (&o)[8], float l, int fq) {
;     l += __shfl_xor(l, 16); l += __shfl_xor(l, 32);
;     const float inv = 1.0f / l;
; #pragma unroll
;     for (int db = 0; db < 8; ++db) { u32x2 w; w.x = cvt_pk(o[db][0] * inv, o[db][1] * inv); w.y = cvt_pk(o[db][2] * inv, o[db][3] * inv); *(u32x2*)(dst + 16 * db + 4 * fq) = w; }
; }
.LBB0_715:
	s_setprio 0
	v_and_b32_e32 v1, 64, v112
	v_xor_b32_e32 v0, 16, v112
	v_add_u32_e32 v1, 64, v1
	v_cmp_lt_i32_e32 vcc, v0, v1
	v_xor_b32_e32 v2, 32, v112
	v_lshlrev_b32_e32 v76, 1, v81
	v_cndmask_b32_e32 v0, v112, v0, vcc
	v_lshlrev_b32_e32 v0, 2, v0
	ds_bpermute_b32 v0, v0, v97
	v_cmp_lt_i32_e32 vcc, v2, v1
	s_waitcnt lgkmcnt(0)
	v_add_f32_e32 v0, v97, v0
	v_cndmask_b32_e32 v1, v112, v2, vcc
	v_lshlrev_b32_e32 v1, 2, v1
	ds_bpermute_b32 v1, v1, v0
	s_waitcnt lgkmcnt(0)
	v_add_f32_e32 v0, v0, v1
	v_div_scale_f32 v1, s[0:1], v0, v0, 1.0
	v_rcp_f32_e32 v2, v1
	v_div_scale_f32 v3, vcc, 1.0, v0, 1.0
	v_fma_f32 v4, -v1, v2, 1.0
	v_fmac_f32_e32 v2, v4, v2
	v_mul_f32_e32 v4, v3, v2
	v_fma_f32 v5, -v1, v4, v3
	v_fmac_f32_e32 v4, v5, v2
	v_fma_f32 v1, -v1, v4, v3
	v_div_fmas_f32 v1, v1, v2, v4
	v_div_fixup_f32 v4, v1, v0, 1.0
	v_mul_f32_e32 v2, v32, v4
	v_mul_f32_e32 v3, v33, v4
	v_cvt_pk_bf16_f32 v2, v2, v3
	v_mul_f32_e32 v3, v34, v4
	v_lshl_add_u64 v[0:1], v[78:79], 0, v[76:77]
	v_mul_f32_e32 v5, v35, v4
	v_cvt_pk_bf16_f32 v3, v3, v5
	global_store_dwordx2 v[0:1], v[2:3], off
	v_mul_f32_e32 v2, v36, v4
	v_mul_f32_e32 v3, v37, v4
	v_cvt_pk_bf16_f32 v2, v2, v3
	v_mul_f32_e32 v3, v38, v4
	v_mul_f32_e32 v5, v39, v4
	v_cvt_pk_bf16_f32 v3, v3, v5
	global_store_dwordx2 v[0:1], v[2:3], off offset:32
	v_mul_f32_e32 v2, v40, v4
	v_mul_f32_e32 v3, v41, v4
	v_cvt_pk_bf16_f32 v2, v2, v3
	v_mul_f32_e32 v3, v42, v4
	v_mul_f32_e32 v5, v43, v4
	v_cvt_pk_bf16_f32 v3, v3, v5
	global_store_dwordx2 v[0:1], v[2:3], off offset:64
	v_mul_f32_e32 v2, v44, v4
	v_mul_f32_e32 v3, v45, v4
	v_cvt_pk_bf16_f32 v2, v2, v3
	v_mul_f32_e32 v3, v46, v4
	v_mul_f32_e32 v5, v47, v4
	v_cvt_pk_bf16_f32 v3, v3, v5
	global_store_dwordx2 v[0:1], v[2:3], off offset:96
	v_mul_f32_e32 v2, v48, v4
	v_mul_f32_e32 v3, v49, v4
	v_cvt_pk_bf16_f32 v2, v2, v3
	v_mul_f32_e32 v3, v50, v4
	v_mul_f32_e32 v5, v51, v4
	v_cvt_pk_bf16_f32 v3, v3, v5
	global_store_dwordx2 v[0:1], v[2:3], off offset:128
	v_mul_f32_e32 v2, v52, v4
	v_mul_f32_e32 v3, v53, v4
	v_cvt_pk_bf16_f32 v2, v2, v3
	v_mul_f32_e32 v3, v54, v4
	v_mul_f32_e32 v5, v55, v4
	v_cvt_pk_bf16_f32 v3, v3, v5
	global_store_dwordx2 v[0:1], v[2:3], off offset:160
	v_mul_f32_e32 v2, v56, v4
	v_mul_f32_e32 v3, v57, v4
	v_cvt_pk_bf16_f32 v2, v2, v3
	v_mul_f32_e32 v3, v58, v4
	v_mul_f32_e32 v5, v59, v4
	v_cvt_pk_bf16_f32 v3, v3, v5
	global_store_dwordx2 v[0:1], v[2:3], off offset:192
	v_mul_f32_e32 v2, v60, v4
	v_mul_f32_e32 v3, v61, v4
	v_cvt_pk_bf16_f32 v2, v2, v3
	v_mul_f32_e32 v3, v62, v4
	v_mul_f32_e32 v4, v63, v4
	v_cvt_pk_bf16_f32 v3, v3, v4
	global_store_dwordx2 v[0:1], v[2:3], off offset:224

; __device__ __forceinline__ int otid() { int t = threadIdx.x; asm volatile("" : "+v"(t)); return t; }
; __device__ __forceinline__ int uni(int x) { return __builtin_amdgcn_readfirstlane(x); }
; #define ATT_LOAD(kt) do { kr[0] = *(const u32x4*)(kbase + (size_t)((kt) * 64 + krow) * NPROJ + kcs); kr[1] = *(const u32x4*)(kbase + (size_t)((kt) * 64 + 32 + krow) * NPROJ + kcs); \
;         vr[0] = *(const u32x4*)(vtb + (size_t)vd * 4096 + (kt) * 64 + vsg); vr[1] = *(const u32x4*)(vtb + (size_t)(64 + vd) * 4096 + (kt) * 64 + vsg); } while (0)
; __device__ __forceinline__ void attn_prompt_item(unsigned char* lds, const Params& p, int item, bool dry) {
;     ...
;     const int cp = item & 31, h = (item >> 5) & 7, b = item >> 8, c0 = 2 * cp;
;     const int tid = otid(), wave = uni(tid >> 6), lane = tid & 63, li = lane & 15, fq = lane >> 4;
;     const int ci = c0 + (wave >> 2), rb = wave & 3;
;     float* tab = (float*)(lds + TAB_OFF);
;     __syncthreads();
;     if (tid < 257) tab[tid] = p.in[10][h * 257 + tid];
;     const int tq_row = ci * 64 + 16 * rb + li;
;     bf16_t* qrow = P + (size_t)(b * TP + tq_row) * NPROJ + C_QB + h * 128;
;     bf16x8 qf[4];
; #pragma unroll
;     for (int ks = 0; ks < 4; ++ks) qf[ks] = *(const bf16x8*)(qrow + 32 * ks + 8 * fq);
;     f32x4 o[8];
; #pragma unroll
;     for (int db = 0; db < 8; ++db) o[db] = (f32x4){0.f, 0.f, 0.f, 0.f};
;     float m = -1e30f, l = 0.f;
;     const int kt0 = (c0 - 8) > 0 ? (c0 - 8) : 0, kt1 = c0 + 1;
;     const bf16_t* kbase = P + (size_t)(b * TP) * NPROJ + C_KB + h * 128;
;     const bf16_t* vtb = (const bf16_t*)((const unsigned char*)p.out + OS_VTB) + (size_t)((b * 8 + h) * 128) * 4096;
;     const int krow = tid >> 4, kcs = (tid & 15) * 8, vd = tid >> 3, vsg = (tid & 7) * 8;
;     u32x4 kr[2], vr[2];
;     ...
;     ATT_LOAD(kt0);
;     for (int kt = kt0; kt <= kt1; ++kt) {
;         unsigned char* bufp = lds + KL_OFF + ((kt - kt0) & 1) * KV_BUF;
;         bf16_t* Kl = (bf16_t*)bufp; bf16_t* VTl = (bf16_t*)(bufp + 17408);
;         *(u32x4*)(Kl + krow * 136 + kcs) = kr[0]; *(u32x4*)(Kl + (32 + krow) * 136 + kcs) = kr[1];
;         *(u32x4*)(VTl + vd * 72 + vsg) = vr[0]; *(u32x4*)(VTl + (64 + vd) * 72 + vsg) = vr[1];
;         if (kt < kt1) ATT_LOAD(kt + 1);
.LBB0_815:
	s_or_b64 exec, exec, s[0:1]
	s_lshl_b32 s0, s73, 1
	s_and_b32 s2, s0, 62
	s_bfe_u32 s0, s29, 0x50001
	s_ashr_i32 s8, s5, 8
	s_lshl_b32 s1, s0, 1
	s_add_i32 s3, s8, s2
	s_min_u32 s9, s1, 8
	s_lshl_b32 s10, s0, 7
	s_lshl_b32 s0, s73, 3
	s_lshr_b32 s1, s5, 2
	s_and_b32 s12, s0, 0x700
	s_lshl_b32 s0, s3, 6
	s_and_b32 s14, s1, 48
	s_ashr_i32 s6, s73, 8
	v_and_b32_e32 v38, 15, v16
	s_or_b32 s0, s0, s14
	v_readlane_b32 s16, v251, 50
	s_waitcnt vmcnt(3)
	v_or_b32_e32 v0, s0, v38
	s_lshl_b32 s5, s6, 12
	v_readlane_b32 s17, v251, 51
	v_add_u32_e32 v2, s5, v0
	s_lshl_b32 s11, s9, 6
	v_mov_b64_e32 v[0:1], s[16:17]
	v_mad_i64_i32 v[0:1], s[0:1], v2, s95, v[0:1]
	s_sub_i32 s13, s10, s11
	s_lshl_b32 s0, s4, 7
	s_lshl_b32 s60, s4, 8
	s_mul_i32 s15, s6, 0x3200000
	s_mul_hi_i32 s1, s5, 0x3200
	s_add_u32 s4, s16, s15
	s_addc_u32 s5, s17, s1
	s_add_u32 s4, s4, s60
	s_addc_u32 s5, s5, 0
	s_add_u32 s4, s4, 0x2000
	s_addc_u32 s5, s5, 0
	s_lshl_b32 s6, s6, 10
	s_or_b32 s6, s0, s6
	s_ashr_i32 s7, s6, 31
	s_lshl_b64 s[6:7], s[6:7], 13
	v_ashrrev_i32_e32 v32, 3, v16
	s_add_u32 s6, s27, s6
	v_lshlrev_b32_e32 v17, 3, v16
	v_ashrrev_i32_e32 v33, 31, v32
	v_bfe_u32 v39, v16, 4, 2
	v_lshl_add_u64 v[0:1], v[0:1], 0, s[60:61]
	s_mov_b64 s[18:19], 0x1800
	s_addc_u32 s7, s59, s7
	v_ashrrev_i32_e32 v40, 4, v16
	v_and_b32_e32 v28, 0x78, v17
	v_and_b32_e32 v18, 56, v17
	v_lshlrev_b64 v[16:17], 13, v[32:33]
	v_sub_u32_e64 v33, s2, 8 clamp
	v_lshl_add_u64 v[78:79], v[0:1], 0, s[18:19]
	v_lshlrev_b32_e32 v76, 4, v39
	v_lshl_add_u64 v[34:35], s[6:7], 0, v[16:17]
	s_mov_b64 s[6:7], 0x80000
	v_lshl_add_u32 v29, v33, 6, v40
	s_waitcnt vmcnt(0)
	v_lshl_add_u64 v[12:13], v[78:79], 0, v[76:77]
	v_lshl_add_u64 v[36:37], v[34:35], 0, s[6:7]
	v_lshlrev_b32_e32 v16, 7, v33
	v_mov_b32_e32 v17, v77
	v_add_u32_e32 v26, 32, v29
	v_mov_b64_e32 v[24:25], s[4:5]
	global_load_dwordx4 v[0:3], v[12:13], off
	global_load_dwordx4 v[4:7], v[12:13], off offset:64
	global_load_dwordx4 v[8:11], v[12:13], off offset:128
	s_nop 0
	global_load_dwordx4 v[12:15], v[12:13], off offset:192
	v_lshlrev_b32_e32 v80, 1, v18
	v_mov_b32_e32 v81, v77
	v_lshl_add_u64 v[18:19], v[36:37], 0, v[16:17]
	v_lshl_add_u64 v[16:17], v[34:35], 0, v[16:17]
	v_mad_i64_i32 v[26:27], s[4:5], v26, s95, v[24:25]
	v_lshlrev_b32_e32 v82, 1, v28
	v_mov_b32_e32 v83, v77
	v_mad_i64_i32 v[24:25], s[4:5], v29, s95, v[24:25]
	v_lshl_add_u64 v[18:19], v[18:19], 0, v[80:81]
	v_lshl_add_u64 v[16:17], v[16:17], 0, v[80:81]
	v_lshl_add_u64 v[26:27], v[26:27], 0, v[82:83]
	v_lshl_add_u64 v[28:29], v[24:25], 0, v[82:83]
	global_load_dwordx4 v[20:23], v[18:19], off
	s_nop 0
	global_load_dwordx4 v[16:19], v[16:17], off
	s_nop 0
	global_load_dwordx4 v[24:27], v[26:27], off
	s_nop 0
	global_load_dwordx4 v[28:31], v[28:29], off
	s_add_i32 s8, s8, s9
	s_lshl_b32 s0, s8, 6
	s_or_b32 s0, s0, s14
	s_sub_i32 s0, s0, 51
	v_lshl_add_u64 v[84:85], v[34:35], 0, v[80:81]
	v_lshl_add_u64 v[86:87], v[36:37], 0, v[80:81]
	v_mul_lo_u32 v83, v32, s94
	v_lshlrev_b32_e32 v81, 2, v39
	v_add_u32_e32 v32, s0, v38
	v_sub_u32_e32 v95, v32, v81
	v_add_u32_e32 v32, s10, v40
	s_or_b32 s0, s15, s12
	v_readfirstlane_b32 s4, v33
	v_subrev_u32_e32 v37, s11, v32
	v_mov_b64_e32 v[32:33], s[0:1]
	v_mul_u32_u24_e32 v93, 0x110, v38
	v_mul_u32_u24_e32 v36, 0x48, v38
	v_mad_i64_i32 v[34:35], s[0:1], v37, s95, v[32:33]
	v_lshlrev_b32_e32 v38, 4, v38
	v_or_b32_e32 v34, v34, v38
	v_lshl_add_u64 v[88:89], s[38:39], 0, v[34:35]
	v_add_u32_e32 v34, 0x60, v37
	v_mad_i64_i32 v[32:33], s[0:1], v34, s95, v[32:33]
	v_or_b32_e32 v32, v32, v38
	v_mov_b32_e32 v97, 0
	v_add_u32_e32 v92, 0x2400, v83
	s_add_i32 s5, s3, -8
	v_mul_lo_u32 v94, v40, s96
	v_lshl_add_u64 v[90:91], s[64:65], 0, v[32:33]
	v_mov_b32_e32 v98, 0xf149f2ca
	v_lshlrev_b32_e32 v96, 1, v36
	s_mov_b32 s60, s13
	v_mov_b32_e32 v32, 0
	v_mov_b32_e32 v33, v97
	v_mov_b32_e32 v34, v97
	v_mov_b32_e32 v35, v97
	v_mov_b32_e32 v36, 0
	v_mov_b32_e32 v37, v97
	v_mov_b32_e32 v38, v97
	v_mov_b32_e32 v39, v97
	v_mov_b32_e32 v40, 0
	v_mov_b32_e32 v41, v97
	v_mov_b32_e32 v42, v97
	v_mov_b32_e32 v43, v97
	v_mov_b32_e32 v44, 0
	v_mov_b32_e32 v45, v97
	v_mov_b32_e32 v46, v97
	v_mov_b32_e32 v47, v97
	v_mov_b32_e32 v48, 0
	v_mov_b32_e32 v49, v97
	v_mov_b32_e32 v50, v97
	v_mov_b32_e32 v51, v97
	v_mov_b32_e32 v52, 0
	v_mov_b32_e32 v53, v97
	v_mov_b32_e32 v54, v97
	v_mov_b32_e32 v55, v97
	v_mov_b32_e32 v56, 0
	v_mov_b32_e32 v57, v97
	v_mov_b32_e32 v58, v97
	v_mov_b32_e32 v59, v97
	v_mov_b32_e32 v60, 0
	v_mov_b32_e32 v61, v97
	v_mov_b32_e32 v62, v97
	v_mov_b32_e32 v63, v97
	v_readfirstlane_b32 s98, v250
	s_lshr_b32 s98, s98, 6
	s_cmp_ge_u32 s98, 4
	s_cbranch_scc0 .Lmy_attn_prio_skip
	s_setprio 1
.Lmy_attn_prio_skip:
	s_branch .LBB0_817
.LBB0_816:
	s_add_i32 s4, s4, 1
	v_subrev_u32_e32 v95, 64, v95
	v_lshl_add_u64 v[88:89], v[88:89], 0, s[68:69]
	s_add_i32 s60, s60, 64
	s_andn2_b64 vcc, exec, s[0:1]
	v_lshl_add_u64 v[90:91], v[90:91], 0, s[68:69]
	s_cbranch_vccz .LBB0_715
